# differential attention unit epilogue: the 32 exchange reads go through a 14-deep window into spare registers instead of a two-deep read-wait-fma ladder
# baseline (speedup 1.0000x reference)
.LBB0_352:
	v_readlane_b32 s6, v252, 46
	v_readlane_b32 s7, v252, 47
	s_andn2_b64 vcc, exec, s[6:7]
	s_waitcnt lgkmcnt(0)
	s_barrier
	s_cbranch_vccnz .LBB0_256
	ds_read2_b32 v[174:175], v95 offset0:114 offset1:115
	ds_read2_b32 v[176:177], v95 offset0:120 offset1:121
	ds_read2_b32 v[178:179], v95 offset0:122 offset1:123
	ds_read2_b32 v[180:181], v95 offset0:10 offset1:11
	ds_read2_b32 v[182:183], v95 offset0:8 offset1:9
	ds_read2_b32 v[184:185], v95 offset0:2 offset1:3
	ds_read2_b32 v[186:187], v95 offset1:1
	ds_read2_b32 v[188:189], v95 offset0:26 offset1:27
	ds_read2_b32 v[190:191], v95 offset0:24 offset1:25
	ds_read2_b32 v[192:193], v95 offset0:18 offset1:19
	ds_read2_b32 v[194:195], v95 offset0:16 offset1:17
	ds_read2_b32 v[196:197], v95 offset0:42 offset1:43
	ds_read2_b32 v[198:199], v95 offset0:40 offset1:41
	ds_read2_b32 v[200:201], v95 offset0:34 offset1:35
	v_lshlrev_b32_e32 v68, 2, v67
	v_ashrrev_i32_e32 v69, 31, v68
	v_readlane_b32 s6, v253, 16
	s_waitcnt lgkmcnt(13)
	v_pk_fma_f32 v[58:59], v[58:59], v[66:67], v[174:175] op_sel_hi:[1,0,1] neg_lo:[0,0,1] neg_hi:[0,0,1]
	ds_read2_b32 v[174:175], v95 offset0:32 offset1:33
	s_waitcnt lgkmcnt(13)
	v_pk_fma_f32 v[64:65], v[60:61], v[66:67], v[176:177] op_sel_hi:[1,0,1] neg_lo:[0,0,1] neg_hi:[0,0,1]
	ds_read2_b32 v[176:177], v95 offset0:58 offset1:59
	s_waitcnt lgkmcnt(13)
	v_pk_fma_f32 v[60:61], v[62:63], v[66:67], v[178:179] op_sel_hi:[1,0,1] neg_lo:[0,0,1] neg_hi:[0,0,1]
	ds_read2_b32 v[178:179], v95 offset0:56 offset1:57
	v_lshlrev_b32_e32 v62, 2, v68
	v_add_u32_e32 v62, 0x20340, v62
	v_pk_mul_f32 v[98:99], v[58:59], v[58:59]
	v_pk_mul_f32 v[100:101], v[64:65], v[64:65]
	s_waitcnt lgkmcnt(13)
	v_pk_fma_f32 v[86:87], v[6:7], v[66:67], v[180:181] op_sel_hi:[1,0,1] neg_lo:[0,0,1] neg_hi:[0,0,1]
	ds_read2_b32 v[180:181], v95 offset0:50 offset1:51
	s_waitcnt lgkmcnt(13)
	v_pk_fma_f32 v[88:89], v[4:5], v[66:67], v[182:183] op_sel_hi:[1,0,1] neg_lo:[0,0,1] neg_hi:[0,0,1]
	ds_read2_b32 v[182:183], v95 offset0:48 offset1:49
	v_pk_mul_f32 v[106:107], v[88:89], v[88:89]
	v_pk_mul_f32 v[104:105], v[86:87], v[86:87]
	s_waitcnt lgkmcnt(13)
	v_pk_fma_f32 v[90:91], v[2:3], v[66:67], v[184:185] op_sel_hi:[1,0,1] neg_lo:[0,0,1] neg_hi:[0,0,1]
	ds_read2_b32 v[184:185], v95 offset0:74 offset1:75
	s_waitcnt lgkmcnt(13)
	v_pk_fma_f32 v[92:93], v[0:1], v[66:67], v[186:187] op_sel_hi:[1,0,1] neg_lo:[0,0,1] neg_hi:[0,0,1]
	ds_read2_b32 v[186:187], v95 offset0:72 offset1:73
	v_pk_mul_f32 v[110:111], v[92:93], v[92:93]
	v_pk_mul_f32 v[108:109], v[90:91], v[90:91]
	s_waitcnt lgkmcnt(13)
	v_pk_fma_f32 v[78:79], v[14:15], v[66:67], v[188:189] op_sel_hi:[1,0,1] neg_lo:[0,0,1] neg_hi:[0,0,1]
	ds_read2_b32 v[188:189], v95 offset0:66 offset1:67
	s_waitcnt lgkmcnt(13)
	v_pk_fma_f32 v[80:81], v[12:13], v[66:67], v[190:191] op_sel_hi:[1,0,1] neg_lo:[0,0,1] neg_hi:[0,0,1]
	ds_read2_b32 v[190:191], v95 offset0:64 offset1:65
	v_pk_mul_f32 v[114:115], v[80:81], v[80:81]
	v_pk_mul_f32 v[112:113], v[78:79], v[78:79]
	s_waitcnt lgkmcnt(13)
	v_pk_fma_f32 v[82:83], v[10:11], v[66:67], v[192:193] op_sel_hi:[1,0,1] neg_lo:[0,0,1] neg_hi:[0,0,1]
	ds_read2_b32 v[192:193], v95 offset0:90 offset1:91
	s_waitcnt lgkmcnt(13)
	v_pk_fma_f32 v[84:85], v[8:9], v[66:67], v[194:195] op_sel_hi:[1,0,1] neg_lo:[0,0,1] neg_hi:[0,0,1]
	ds_read2_b32 v[194:195], v95 offset0:88 offset1:89
	v_pk_mul_f32 v[118:119], v[84:85], v[84:85]
	v_pk_mul_f32 v[116:117], v[82:83], v[82:83]
	s_waitcnt lgkmcnt(13)
	v_pk_fma_f32 v[70:71], v[22:23], v[66:67], v[196:197] op_sel_hi:[1,0,1] neg_lo:[0,0,1] neg_hi:[0,0,1]
	ds_read2_b32 v[196:197], v95 offset0:82 offset1:83
	s_waitcnt lgkmcnt(13)
	v_pk_fma_f32 v[72:73], v[20:21], v[66:67], v[198:199] op_sel_hi:[1,0,1] neg_lo:[0,0,1] neg_hi:[0,0,1]
	ds_read2_b32 v[198:199], v95 offset0:80 offset1:81
	v_pk_mul_f32 v[122:123], v[72:73], v[72:73]
	v_pk_mul_f32 v[120:121], v[70:71], v[70:71]
	s_waitcnt lgkmcnt(13)
	v_pk_fma_f32 v[74:75], v[18:19], v[66:67], v[200:201] op_sel_hi:[1,0,1] neg_lo:[0,0,1] neg_hi:[0,0,1]
	ds_read2_b32 v[200:201], v95 offset0:106 offset1:107
	s_waitcnt lgkmcnt(13)
	v_pk_fma_f32 v[76:77], v[16:17], v[66:67], v[174:175] op_sel_hi:[1,0,1] neg_lo:[0,0,1] neg_hi:[0,0,1]
	ds_read2_b32 v[174:175], v95 offset0:104 offset1:105
	v_pk_mul_f32 v[126:127], v[76:77], v[76:77]
	v_pk_mul_f32 v[124:125], v[74:75], v[74:75]
	s_waitcnt lgkmcnt(13)
	v_pk_fma_f32 v[30:31], v[30:31], v[66:67], v[176:177] op_sel_hi:[1,0,1] neg_lo:[0,0,1] neg_hi:[0,0,1]
	ds_read2_b32 v[176:177], v95 offset0:98 offset1:99
	s_waitcnt lgkmcnt(13)
	v_pk_fma_f32 v[28:29], v[28:29], v[66:67], v[178:179] op_sel_hi:[1,0,1] neg_lo:[0,0,1] neg_hi:[0,0,1]
	ds_read2_b32 v[178:179], v95 offset0:96 offset1:97
	v_pk_mul_f32 v[130:131], v[28:29], v[28:29]
	v_pk_mul_f32 v[128:129], v[30:31], v[30:31]
	s_waitcnt lgkmcnt(13)
	v_pk_fma_f32 v[26:27], v[26:27], v[66:67], v[180:181] op_sel_hi:[1,0,1] neg_lo:[0,0,1] neg_hi:[0,0,1]
	ds_read2_b32 v[180:181], v95 offset0:112 offset1:113
	s_waitcnt lgkmcnt(13)
	v_pk_fma_f32 v[68:69], v[24:25], v[66:67], v[182:183] op_sel_hi:[1,0,1] neg_lo:[0,0,1] neg_hi:[0,0,1]
	v_pk_mul_f32 v[134:135], v[68:69], v[68:69]
	v_pk_mul_f32 v[132:133], v[26:27], v[26:27]
	s_waitcnt lgkmcnt(12)
	v_pk_fma_f32 v[18:19], v[38:39], v[66:67], v[184:185] op_sel_hi:[1,0,1] neg_lo:[0,0,1] neg_hi:[0,0,1]
	s_waitcnt lgkmcnt(11)
	v_pk_fma_f32 v[20:21], v[36:37], v[66:67], v[186:187] op_sel_hi:[1,0,1] neg_lo:[0,0,1] neg_hi:[0,0,1]
	v_add_f32_e32 v36, v110, v111
	v_add_f32_e32 v36, v36, v108
	v_add_f32_e32 v36, v36, v109
	v_add_f32_e32 v36, v36, v106
	v_add_f32_e32 v36, v36, v107
	v_add_f32_e32 v36, v36, v104
	v_add_f32_e32 v36, v36, v105
	v_add_f32_e32 v36, v36, v118
	v_add_f32_e32 v36, v36, v119
	v_add_f32_e32 v36, v36, v116
	v_add_f32_e32 v36, v36, v117
	v_add_f32_e32 v36, v36, v114
	v_add_f32_e32 v36, v36, v115
	v_add_f32_e32 v36, v36, v112
	v_add_f32_e32 v36, v36, v113
	v_add_f32_e32 v36, v36, v126
	s_waitcnt lgkmcnt(10)
	v_pk_fma_f32 v[22:23], v[34:35], v[66:67], v[188:189] op_sel_hi:[1,0,1] neg_lo:[0,0,1] neg_hi:[0,0,1]
	s_waitcnt lgkmcnt(9)
	v_pk_fma_f32 v[24:25], v[32:33], v[66:67], v[190:191] op_sel_hi:[1,0,1] neg_lo:[0,0,1] neg_hi:[0,0,1]
	v_add_f32_e32 v36, v36, v127
	v_add_f32_e32 v36, v36, v124
	v_add_f32_e32 v36, v36, v125
	v_add_f32_e32 v36, v36, v122
	v_add_f32_e32 v36, v36, v123
	s_waitcnt lgkmcnt(8)
	v_pk_fma_f32 v[10:11], v[46:47], v[66:67], v[192:193] op_sel_hi:[1,0,1] neg_lo:[0,0,1] neg_hi:[0,0,1]
	s_waitcnt lgkmcnt(7)
	v_pk_fma_f32 v[12:13], v[44:45], v[66:67], v[194:195] op_sel_hi:[1,0,1] neg_lo:[0,0,1] neg_hi:[0,0,1]
	v_add_f32_e32 v36, v36, v120
	v_add_f32_e32 v36, v36, v121
	v_add_f32_e32 v36, v36, v134
	v_add_f32_e32 v36, v36, v135
	v_add_f32_e32 v36, v36, v132
	s_waitcnt lgkmcnt(6)
	v_pk_fma_f32 v[14:15], v[42:43], v[66:67], v[196:197] op_sel_hi:[1,0,1] neg_lo:[0,0,1] neg_hi:[0,0,1]
	s_waitcnt lgkmcnt(5)
	v_pk_fma_f32 v[16:17], v[40:41], v[66:67], v[198:199] op_sel_hi:[1,0,1] neg_lo:[0,0,1] neg_hi:[0,0,1]
	v_add_f32_e32 v36, v36, v133
	v_add_f32_e32 v36, v36, v130
	v_add_f32_e32 v36, v36, v131
	v_add_f32_e32 v36, v36, v128
	v_pk_mul_f32 v[32:33], v[24:25], v[24:25]
	v_add_f32_e32 v36, v36, v129
	s_waitcnt lgkmcnt(4)
	v_pk_fma_f32 v[2:3], v[54:55], v[66:67], v[200:201] op_sel_hi:[1,0,1] neg_lo:[0,0,1] neg_hi:[0,0,1]
	s_waitcnt lgkmcnt(3)
	v_pk_fma_f32 v[4:5], v[52:53], v[66:67], v[174:175] op_sel_hi:[1,0,1] neg_lo:[0,0,1] neg_hi:[0,0,1]
	s_waitcnt lgkmcnt(2)
	v_pk_fma_f32 v[6:7], v[50:51], v[66:67], v[176:177] op_sel_hi:[1,0,1] neg_lo:[0,0,1] neg_hi:[0,0,1]
	s_waitcnt lgkmcnt(1)
	v_pk_fma_f32 v[8:9], v[48:49], v[66:67], v[178:179] op_sel_hi:[1,0,1] neg_lo:[0,0,1] neg_hi:[0,0,1]
	s_waitcnt lgkmcnt(0)
	v_pk_fma_f32 v[0:1], v[56:57], v[66:67], v[180:181] op_sel_hi:[1,0,1] neg_lo:[0,0,1] neg_hi:[0,0,1]
	v_add_f32_e32 v32, v36, v32
	v_mbcnt_lo_u32_b32 v66, -1, 0
	v_mbcnt_hi_u32_b32 v66, -1, v66
	ds_read_b128 v[36:39], v62
	ds_read_b128 v[40:43], v62 offset:32
	v_pk_mul_f32 v[34:35], v[22:23], v[22:23]
	v_add_f32_e32 v32, v32, v33
	v_add_f32_e32 v32, v32, v34
	v_pk_mul_f32 v[138:139], v[20:21], v[20:21]
	v_add_f32_e32 v32, v32, v35
	v_add_f32_e32 v32, v32, v138
	v_pk_mul_f32 v[136:137], v[18:19], v[18:19]
	v_add_f32_e32 v32, v32, v139
	v_add_f32_e32 v32, v32, v136
	v_pk_mul_f32 v[142:143], v[16:17], v[16:17]
	v_add_f32_e32 v32, v32, v137
	v_add_f32_e32 v32, v32, v142
	v_pk_mul_f32 v[140:141], v[14:15], v[14:15]
	v_add_f32_e32 v32, v32, v143
	v_add_f32_e32 v32, v32, v140
	v_pk_mul_f32 v[44:45], v[12:13], v[12:13]
	v_add_f32_e32 v32, v32, v141
	v_add_f32_e32 v32, v32, v44
	v_pk_mul_f32 v[46:47], v[10:11], v[10:11]
	v_add_f32_e32 v32, v32, v45
	v_add_f32_e32 v32, v32, v46
	v_pk_mul_f32 v[48:49], v[8:9], v[8:9]
	v_add_f32_e32 v32, v32, v47
	v_add_f32_e32 v32, v32, v48
	v_pk_mul_f32 v[50:51], v[6:7], v[6:7]
	v_add_f32_e32 v32, v32, v49
	v_add_f32_e32 v32, v32, v50
	v_pk_mul_f32 v[52:53], v[4:5], v[4:5]
	v_add_f32_e32 v32, v32, v51
	v_add_f32_e32 v32, v32, v52
	v_pk_mul_f32 v[54:55], v[2:3], v[2:3]
	v_add_f32_e32 v32, v32, v53
	v_add_f32_e32 v32, v32, v54
	v_pk_mul_f32 v[56:57], v[0:1], v[0:1]
	v_add_f32_e32 v32, v32, v55
	v_add_f32_e32 v32, v32, v56
	v_add_f32_e32 v32, v32, v57
	v_add_f32_e32 v32, v32, v98
	v_add_f32_e32 v32, v32, v99
	v_add_f32_e32 v32, v32, v100
	v_pk_mul_f32 v[102:103], v[60:61], v[60:61]
	v_add_f32_e32 v32, v32, v101
	v_add_f32_e32 v32, v32, v102
	v_add_f32_e32 v34, v32, v103
	v_lshlrev_b32_e32 v32, 2, v66
	v_xor_b32_e32 v32, 0x80, v32
	ds_bpermute_b32 v35, v32, v34
	v_or_b32_e32 v32, s30, v94
	v_mov_b32_e32 v33, s31
	v_lshlrev_b64 v[32:33], 11, v[32:33]
	v_readlane_b32 s7, v253, 17
	s_waitcnt lgkmcnt(0)
	v_add_f32_e32 v34, v34, v35
	v_fmamk_f32 v34, v34, 0x3c000000, v217
	v_mul_f32_e32 v35, 0x4f800000, v34
	v_cmp_gt_f32_e32 vcc, s79, v34
	v_lshl_add_u64 v[32:33], s[6:7], 0, v[32:33]
	v_lshl_add_u64 v[32:33], s[20:21], 1, v[32:33]
	v_cndmask_b32_e32 v34, v34, v35, vcc
	v_sqrt_f32_e32 v35, v34
	s_nop 0
	v_add_u32_e32 v44, -1, v35
	v_fma_f32 v45, -v44, v35, v34
	v_cmp_ge_f32_e64 s[10:11], 0, v45
	v_add_u32_e32 v45, 1, v35
	s_nop 0
	v_cndmask_b32_e64 v44, v35, v44, s[10:11]
	v_fma_f32 v35, -v45, v35, v34
	v_cmp_lt_f32_e64 s[10:11], 0, v35
	s_nop 1
	v_cndmask_b32_e64 v35, v44, v45, s[10:11]
	v_mul_f32_e32 v44, 0x37800000, v35
	v_cndmask_b32_e32 v35, v35, v44, vcc
	v_cmp_class_f32_e32 vcc, v34, v215
	s_nop 1
	v_cndmask_b32_e32 v44, v35, v34, vcc
	v_div_scale_f32 v45, s[6:7], v44, v44, 1.0
	v_rcp_f32_e32 v46, v45
	v_lshlrev_b32_e32 v34, 3, v67
	v_ashrrev_i32_e32 v35, 31, v34
	v_lshl_add_u64 v[32:33], v[34:35], 1, v[32:33]
	v_fma_f32 v34, -v45, v46, 1.0
	v_fmac_f32_e32 v46, v34, v46
	v_div_scale_f32 v34, vcc, 1.0, v44, 1.0
	v_mul_f32_e32 v35, v34, v46
	v_fma_f32 v47, -v45, v35, v34
	v_fmac_f32_e32 v35, v47, v46
	v_fma_f32 v34, -v45, v35, v34
	v_div_fmas_f32 v34, v34, v46, v35
	v_div_fixup_f32 v34, v34, v44, 1.0
	v_mul_f32_e32 v34, v151, v34
	v_pk_mul_f32 v[44:45], v[92:93], v[34:35] op_sel_hi:[1,0]
	v_pk_mul_f32 v[46:47], v[74:75], v[34:35] op_sel_hi:[1,0]
	s_waitcnt lgkmcnt(1)
	v_pk_mul_f32 v[36:37], v[36:37], v[44:45]
	v_pk_mul_f32 v[44:45], v[90:91], v[34:35] op_sel_hi:[1,0]
	v_cvt_pk_bf16_f32 v36, v36, v37
	v_pk_mul_f32 v[38:39], v[38:39], v[44:45]
	v_pk_mul_f32 v[44:45], v[84:85], v[34:35] op_sel_hi:[1,0]
	v_cvt_pk_bf16_f32 v37, v38, v39
	v_pk_mul_f32 v[38:39], v[88:89], v[34:35] op_sel_hi:[1,0]
	v_pk_mul_f32 v[48:49], v[72:73], v[34:35] op_sel_hi:[1,0]
	s_waitcnt lgkmcnt(0)
	v_pk_mul_f32 v[38:39], v[40:41], v[38:39]
	v_pk_mul_f32 v[40:41], v[86:87], v[34:35] op_sel_hi:[1,0]
	v_cvt_pk_bf16_f32 v38, v38, v39
	v_pk_mul_f32 v[40:41], v[42:43], v[40:41]
	s_nop 0
	v_permlane32_swap_b32_e32 v36, v38
	v_cvt_pk_bf16_f32 v39, v40, v41
	s_nop 1
	v_permlane32_swap_b32_e32 v37, v39
	global_store_dwordx4 v[32:33], v[36:39], off
	s_nop 0
	ds_read_b128 v[36:39], v62 offset:64
	s_nop 0
	ds_read_b128 v[40:43], v62 offset:96
	v_pk_mul_f32 v[50:51], v[70:71], v[34:35] op_sel_hi:[1,0]
	v_pk_mul_f32 v[26:27], v[26:27], v[34:35] op_sel_hi:[1,0]
	v_pk_mul_f32 v[28:29], v[28:29], v[34:35] op_sel_hi:[1,0]
	v_pk_mul_f32 v[30:31], v[30:31], v[34:35] op_sel_hi:[1,0]
	v_pk_mul_f32 v[24:25], v[24:25], v[34:35] op_sel_hi:[1,0]
	v_pk_mul_f32 v[22:23], v[22:23], v[34:35] op_sel_hi:[1,0]
	v_pk_mul_f32 v[20:21], v[20:21], v[34:35] op_sel_hi:[1,0]
	v_pk_mul_f32 v[18:19], v[18:19], v[34:35] op_sel_hi:[1,0]
	v_pk_mul_f32 v[16:17], v[16:17], v[34:35] op_sel_hi:[1,0]
	v_pk_mul_f32 v[14:15], v[14:15], v[34:35] op_sel_hi:[1,0]
	v_pk_mul_f32 v[12:13], v[12:13], v[34:35] op_sel_hi:[1,0]
	v_pk_mul_f32 v[10:11], v[10:11], v[34:35] op_sel_hi:[1,0]
	v_pk_mul_f32 v[8:9], v[8:9], v[34:35] op_sel_hi:[1,0]
	v_pk_mul_f32 v[6:7], v[6:7], v[34:35] op_sel_hi:[1,0]
	v_pk_mul_f32 v[4:5], v[4:5], v[34:35] op_sel_hi:[1,0]
	v_pk_mul_f32 v[2:3], v[2:3], v[34:35] op_sel_hi:[1,0]
	v_pk_mul_f32 v[0:1], v[0:1], v[34:35] op_sel_hi:[1,0]
	s_waitcnt lgkmcnt(1)
	v_pk_mul_f32 v[36:37], v[36:37], v[44:45]
	v_pk_mul_f32 v[44:45], v[82:83], v[34:35] op_sel_hi:[1,0]
	v_cvt_pk_bf16_f32 v36, v36, v37
	v_pk_mul_f32 v[38:39], v[38:39], v[44:45]
	v_pk_mul_f32 v[44:45], v[76:77], v[34:35] op_sel_hi:[1,0]
	v_cvt_pk_bf16_f32 v37, v38, v39
	v_pk_mul_f32 v[38:39], v[80:81], v[34:35] op_sel_hi:[1,0]
	s_waitcnt lgkmcnt(0)
	v_pk_mul_f32 v[38:39], v[40:41], v[38:39]
	v_pk_mul_f32 v[40:41], v[78:79], v[34:35] op_sel_hi:[1,0]
	v_cvt_pk_bf16_f32 v38, v38, v39
	v_pk_mul_f32 v[40:41], v[42:43], v[40:41]
	s_nop 0
	v_permlane32_swap_b32_e32 v36, v38
	v_cvt_pk_bf16_f32 v39, v40, v41
	s_nop 1
	v_permlane32_swap_b32_e32 v37, v39
	global_store_dwordx4 v[32:33], v[36:39], off offset:32
	s_nop 0
	ds_read_b128 v[36:39], v62 offset:128
	s_nop 0
	ds_read_b128 v[40:43], v62 offset:160
	s_waitcnt lgkmcnt(1)
	v_pk_mul_f32 v[36:37], v[44:45], v[36:37]
	v_pk_mul_f32 v[38:39], v[46:47], v[38:39]
	s_waitcnt lgkmcnt(0)
	v_pk_mul_f32 v[40:41], v[48:49], v[40:41]
	v_pk_mul_f32 v[42:43], v[50:51], v[42:43]
	v_cvt_pk_bf16_f32 v36, v36, v37
	v_cvt_pk_bf16_f32 v37, v38, v39
	v_cvt_pk_bf16_f32 v38, v40, v41
	v_cvt_pk_bf16_f32 v39, v42, v43
	s_nop 0
	v_permlane32_swap_b32_e32 v36, v38
	v_permlane32_swap_b32_e32 v37, v39
	global_store_dwordx4 v[32:33], v[36:39], off offset:64
	s_nop 0
	ds_read_b128 v[36:39], v62 offset:192
	s_nop 0
	ds_read_b128 v[40:43], v62 offset:224
	v_pk_mul_f32 v[44:45], v[68:69], v[34:35] op_sel_hi:[1,0]
	s_waitcnt lgkmcnt(1)
	v_pk_mul_f32 v[38:39], v[26:27], v[38:39]
	v_pk_mul_f32 v[36:37], v[44:45], v[36:37]
	s_waitcnt lgkmcnt(0)
	v_pk_mul_f32 v[28:29], v[28:29], v[40:41]
	v_pk_mul_f32 v[30:31], v[30:31], v[42:43]
	v_cvt_pk_bf16_f32 v26, v36, v37
	v_cvt_pk_bf16_f32 v27, v38, v39
	v_cvt_pk_bf16_f32 v28, v28, v29
	v_cvt_pk_bf16_f32 v29, v30, v31
	s_nop 0
	v_permlane32_swap_b32_e32 v26, v28
	v_permlane32_swap_b32_e32 v27, v29
	global_store_dwordx4 v[32:33], v[26:29], off offset:96
	s_nop 0
	ds_read_b128 v[26:29], v62 offset:256
	s_nop 0
	ds_read_b128 v[36:39], v62 offset:288
	s_waitcnt lgkmcnt(1)
	v_pk_mul_f32 v[24:25], v[24:25], v[26:27]
	v_pk_mul_f32 v[22:23], v[22:23], v[28:29]
	s_waitcnt lgkmcnt(0)
	v_pk_mul_f32 v[20:21], v[20:21], v[36:37]
	v_pk_mul_f32 v[26:27], v[18:19], v[38:39]
	v_cvt_pk_bf16_f32 v18, v24, v25
	v_cvt_pk_bf16_f32 v19, v22, v23
	v_cvt_pk_bf16_f32 v20, v20, v21
	v_cvt_pk_bf16_f32 v21, v26, v27
	s_nop 0
	v_permlane32_swap_b32_e32 v18, v20
	v_permlane32_swap_b32_e32 v19, v21
	global_store_dwordx4 v[32:33], v[18:21], off offset:128
	s_nop 0
	ds_read_b128 v[18:21], v62 offset:320
	s_nop 0
	ds_read_b128 v[22:25], v62 offset:352
	s_waitcnt lgkmcnt(1)
	v_pk_mul_f32 v[16:17], v[16:17], v[18:19]
	v_pk_mul_f32 v[14:15], v[14:15], v[20:21]
	s_waitcnt lgkmcnt(0)
	v_pk_mul_f32 v[12:13], v[12:13], v[22:23]
	v_pk_mul_f32 v[18:19], v[10:11], v[24:25]
	v_cvt_pk_bf16_f32 v10, v16, v17
	v_cvt_pk_bf16_f32 v11, v14, v15
	v_cvt_pk_bf16_f32 v12, v12, v13
	v_cvt_pk_bf16_f32 v13, v18, v19
	s_nop 0
	v_permlane32_swap_b32_e32 v10, v12
	v_permlane32_swap_b32_e32 v11, v13
	global_store_dwordx4 v[32:33], v[10:13], off offset:160
	s_nop 0
	ds_read_b128 v[10:13], v62 offset:384
	s_nop 0
	ds_read_b128 v[14:17], v62 offset:416
	s_waitcnt lgkmcnt(1)
	v_pk_mul_f32 v[8:9], v[8:9], v[10:11]
	v_pk_mul_f32 v[6:7], v[6:7], v[12:13]
	s_waitcnt lgkmcnt(0)
	v_pk_mul_f32 v[4:5], v[4:5], v[14:15]
	v_pk_mul_f32 v[10:11], v[2:3], v[16:17]
	v_cvt_pk_bf16_f32 v2, v8, v9
	v_cvt_pk_bf16_f32 v3, v6, v7
	v_cvt_pk_bf16_f32 v4, v4, v5
	v_cvt_pk_bf16_f32 v5, v10, v11
	s_nop 0
	v_permlane32_swap_b32_e32 v2, v4
	v_permlane32_swap_b32_e32 v3, v5
	global_store_dwordx4 v[32:33], v[2:5], off offset:192
	s_nop 0
	ds_read_b128 v[2:5], v62 offset:448
	s_nop 0
	ds_read_b128 v[6:9], v62 offset:480
	v_pk_mul_f32 v[10:11], v[58:59], v[34:35] op_sel_hi:[1,0]
	v_pk_mul_f32 v[12:13], v[64:65], v[34:35] op_sel_hi:[1,0]
	v_pk_mul_f32 v[14:15], v[60:61], v[34:35] op_sel_hi:[1,0]
	s_waitcnt lgkmcnt(1)
	v_pk_mul_f32 v[0:1], v[0:1], v[2:3]
	v_pk_mul_f32 v[2:3], v[10:11], v[4:5]
	s_waitcnt lgkmcnt(0)
	v_pk_mul_f32 v[4:5], v[12:13], v[6:7]
	v_pk_mul_f32 v[6:7], v[14:15], v[8:9]
	v_cvt_pk_bf16_f32 v0, v0, v1
	v_cvt_pk_bf16_f32 v1, v2, v3
	v_cvt_pk_bf16_f32 v2, v4, v5
	v_cvt_pk_bf16_f32 v3, v6, v7
	s_nop 0
	v_permlane32_swap_b32_e32 v0, v2
	v_permlane32_swap_b32_e32 v1, v3
	global_store_dwordx4 v[32:33], v[0:3], off offset:224
	s_branch .LBB0_256
